# v62 + P1: workgroups 128-255 run their weight-conversion half-round BEFORE their five GEMM units (de-phases the two halves of P1 at no extra time)
# baseline (speedup 1.0000x reference)
.LBB0_135:
	s_cmp_lt_i32 s81, 2
	s_cselect_b64 s[2:3], -1, 0
	s_and_b64 s[16:17], s[2:3], s[0:1]
	s_andn2_b64 vcc, exec, s[16:17]
	s_cbranch_vccnz .LBB0_208
	s_cmpk_lg_i32 s79, 0x100
	s_cbranch_scc1 .Lp1_gemm_start
	s_cmpk_lt_i32 s82, 0x80
	s_cbranch_scc1 .Lp1_gemm_start
	v_mbcnt_hi_u32_b32 v128, -1, v187
	s_branch .Lp1_conv_entry
.Lp1_gemm_start:
	s_mov_b64 s[0:1], s[70:71]
	s_and_b32 s4, s80, 0xffffffc0
	v_mbcnt_hi_u32_b32 v128, -1, v187
	s_load_dwordx2 s[2:3], s[0:1], 0xb8
	s_movk_i32 s0, 0x800
	v_add_u32_e32 v0, s4, v128
	v_cmp_gt_i32_e32 vcc, s0, v0
	s_waitcnt lgkmcnt(0)
	s_and_saveexec_b64 s[0:1], vcc
	s_cbranch_execz .LBB0_139
	s_and_b32 s5, s82, 7
	s_lshl_b32 s6, s5, 13
	v_mov_b32_e32 v129, 0
	s_ashr_i32 s5, s4, 31
	v_add_u32_e32 v2, 0xfffffe00, v0
	v_lshl_add_u64 v[0:1], v[128:129], 0, s[4:5]
	s_add_u32 s4, s2, s6
	s_addc_u32 s5, s3, 0
	v_lshl_add_u64 v[0:1], v[0:1], 2, s[4:5]
	s_mov_b64 s[4:5], 0x100000
	v_lshl_add_u64 v[0:1], v[0:1], 0, s[4:5]
	s_lshl_b32 s4, s83, 8
	s_add_i32 s4, s4, 0
	v_lshl_add_u32 v3, v128, 2, s4
	v_add_u32_e32 v3, 0x20000, v3
	s_mov_b64 s[4:5], 0
	s_mov_b64 s[6:7], 0x800
	s_movk_i32 s8, 0x5ff

.LBB0_158:
	s_cmpk_eq_i32 s79, 0x100
	s_cselect_b64 s[0:1], -1, 0
	s_cmpk_gt_i32 s82, 0x7f
	s_cselect_b64 s[2:3], -1, 0
	s_and_b64 s[0:1], s[2:3], s[0:1]
	s_and_b64 vcc, exec, s[0:1]
	s_branch .LBB0_208
.Lp1_conv_entry:
	s_mov_b64 s[2:3], s[70:71]
	s_load_dwordx2 s[0:1], s[2:3], 0xb8
	s_lshl_b32 s6, s82, 3
	s_lshl_b32 s5, s83, 14
	s_add_i32 s13, s6, s83
	s_add_i32 s5, s5, 0
	s_addk_i32 s13, 0xfc00
	s_waitcnt lgkmcnt(0)
	s_add_u32 s18, s0, 0x1500000
	s_addc_u32 s19, s1, 0
	s_add_u32 s20, s0, 0x1b00000
	s_addc_u32 s21, s1, 0
	s_add_u32 s22, s0, 0x2e00000
	s_addc_u32 s23, s1, 0
	s_add_u32 s24, s0, 0x2d00000
	s_addc_u32 s25, s1, 0
	s_add_u32 s26, s0, 0x2c00000
	s_addc_u32 s27, s1, 0
	s_add_u32 s28, s0, 0x2b00000
	s_addc_u32 s29, s1, 0
	v_lshrrev_b32_e32 v40, 3, v128
	v_and_b32_e32 v4, 64, v128
	s_add_u32 s30, s0, 0x2a00000
	v_add_u32_e32 v41, 8, v40
	v_or_b32_e32 v5, v40, v4
	s_addc_u32 s31, s1, 0
	v_lshlrev_b32_e32 v0, 2, v128
	v_or_b32_e32 v42, 16, v40
	v_lshlrev_b32_e32 v2, 3, v128
	v_lshlrev_b32_e32 v45, 2, v5
	v_or_b32_e32 v5, v41, v4
	s_add_u32 s34, s0, 0x2600000
	v_and_b32_e32 v0, 28, v0
	v_add_u32_e32 v43, 24, v40
	v_add_u32_e32 v6, 56, v40
	v_and_b32_e32 v2, 56, v2
	v_lshlrev_b32_e32 v46, 2, v5
	v_or_b32_e32 v5, v42, v4
	s_addc_u32 s35, s1, 0
	v_lshl_add_u32 v1, v0, 2, s5
	v_mul_u32_u24_e32 v3, 0x84, v40
	v_mul_u32_u24_e32 v7, 0x84, v2
	v_lshlrev_b32_e32 v8, 2, v40
	v_lshlrev_b32_e32 v47, 2, v5
	v_or_b32_e32 v5, v43, v4
	v_and_or_b32 v4, v6, 63, v4
	s_lshl_b32 s15, s82, 9
	s_lshl_b32 s0, s83, 6
	s_mov_b32 s4, 0
	v_mov_b32_e32 v33, 0
	v_add3_u32 v44, s5, v7, v8
	v_lshlrev_b32_e32 v48, 2, v5
	v_or_b32_e32 v49, 0x80, v45
	v_add_u32_e32 v50, 0xa0, v45
	v_or_b32_e32 v51, 0xc0, v45
	v_lshlrev_b32_e32 v52, 2, v4
	s_add_i32 s15, s15, s0
	v_or_b32_e32 v53, 0xffff0000, v128
	s_mov_b32 s33, 1
	v_lshlrev_b32_e32 v32, 1, v2
	v_lshlrev_b32_e32 v34, 2, v0
	v_add_u32_e32 v54, v1, v3
	s_mov_b32 s40, 0
	s_branch .LBB0_161

.LBB0_207:
	s_waitcnt vmcnt(0) lgkmcnt(0)
	s_barrier
	s_branch .Lp1_gemm_start
